# fill_row_scales rewritten by hand: wave-uniform unit->row-tile map on the SALU, all rows partial-sum loads issued before the first wait (on top of tile-transition barrier change)
# speedup vs baseline: 1.0064x; 1.0064x over previous
.LBB0_194:
	s_waitcnt lgkmcnt(0)
	s_add_u32 s18, s70, 0x1b700000
	s_addc_u32 s19, s71, 0
	s_add_u32 s14, s70, 0x7700000
	s_addc_u32 s15, s71, 0
	s_add_u32 s16, s70, 0xf700000
	s_addc_u32 s17, s71, 0
	s_cmp_lt_i32 s74, 3
	s_cselect_b64 s[0:1], -1, 0
	s_cmp_gt_i32 s75, 2
	s_cselect_b64 s[4:5], -1, 0
	s_and_b64 s[0:1], s[0:1], s[4:5]
	s_andn2_b64 vcc, exec, s[0:1]
	v_lshrrev_b32_e32 v129, 8, v128
	s_cbranch_vccnz .LBB0_303
	v_lshlrev_b32_e32 v8, 2, v128
	s_ashr_i32 s3, s2, 31
	v_add_u32_e32 v0, 0, v8
	s_ashr_i32 s56, s72, 31
	s_mov_b32 s57, s72
	v_and_b32_e32 v4, 0xff, v128
	v_add_u32_e32 v5, 0xfffffe00, v128
	v_add_u32_e32 v6, 0x20000, v0
	v_lshrrev_b32_e32 v7, 8, v128
	s_mov_b64 s[0:1], 0
	v_mov_b64_e32 v[0:1], s[2:3]
	s_mov_b64 s[4:5], 0x600
	s_mov_b32 s10, 0x2aaaaaab
	s_movk_i32 s11, 0x60
	v_mov_b32_e32 v9, 0x358637bd
	s_movk_i32 s12, 0x8ff
	v_mov_b32_e32 v10, 0xc0
	v_mov_b32_e32 v11, 0xc1
	v_and_b32_e32 v110, 0xff, v128
	s_lshr_b32 s98, s91, 2
	v_mov_b32_e32 v111, 0x358637bd
	s_mul_i32 s99, s98, s72
	s_add_i32 s99, s99, s2
	s_cmp_lt_u32 s99, 0x600
	s_cselect_b32 s99, s99, s2
	s_and_b32 s100, s99, 7
	s_mul_i32 s100, s100, 0xc0
	s_lshr_b32 s101, s99, 3
	s_add_i32 s100, s100, s101
	s_mul_hi_u32 s101, s100, 0x2aaaaab
	s_lshl_b32 s101, s101, 3
	s_and_b32 s100, s100, 7
	s_or_b32 s101, s101, s100
	s_lshl_b32 s101, s101, 8
	v_add_u32_e32 v108, s101, v110
	v_lshlrev_b32_e32 v108, 6, v108
	v_mov_b32_e32 v109, 0
	v_lshl_add_u64 v[108:109], s[18:19], 0, v[108:109]
	global_load_dwordx4 v[12:15], v[108:109], off
	global_load_dwordx4 v[16:19], v[108:109], off offset:16
	global_load_dwordx4 v[20:23], v[108:109], off offset:32
	global_load_dwordx4 v[24:27], v[108:109], off offset:48
	s_add_i32 s98, s98, 2
	s_mul_i32 s99, s98, s72
	s_add_i32 s99, s99, s2
	s_cmp_lt_u32 s99, 0x600
	s_cselect_b32 s99, s99, s2
	s_and_b32 s100, s99, 7
	s_mul_i32 s100, s100, 0xc0
	s_lshr_b32 s101, s99, 3
	s_add_i32 s100, s100, s101
	s_mul_hi_u32 s101, s100, 0x2aaaaab
	s_lshl_b32 s101, s101, 3
	s_and_b32 s100, s100, 7
	s_or_b32 s101, s101, s100
	s_lshl_b32 s101, s101, 8
	v_add_u32_e32 v108, s101, v110
	v_lshlrev_b32_e32 v108, 6, v108
	v_mov_b32_e32 v109, 0
	v_lshl_add_u64 v[108:109], s[18:19], 0, v[108:109]
	global_load_dwordx4 v[28:31], v[108:109], off
	global_load_dwordx4 v[32:35], v[108:109], off offset:16
	global_load_dwordx4 v[36:39], v[108:109], off offset:32
	global_load_dwordx4 v[40:43], v[108:109], off offset:48
	s_add_i32 s98, s98, 2
	s_mul_i32 s99, s98, s72
	s_add_i32 s99, s99, s2
	s_cmp_lt_u32 s99, 0x600
	s_cselect_b32 s99, s99, s2
	s_and_b32 s100, s99, 7
	s_mul_i32 s100, s100, 0xc0
	s_lshr_b32 s101, s99, 3
	s_add_i32 s100, s100, s101
	s_mul_hi_u32 s101, s100, 0x2aaaaab
	s_lshl_b32 s101, s101, 3
	s_and_b32 s100, s100, 7
	s_or_b32 s101, s101, s100
	s_lshl_b32 s101, s101, 8
	v_add_u32_e32 v108, s101, v110
	v_lshlrev_b32_e32 v108, 6, v108
	v_mov_b32_e32 v109, 0
	v_lshl_add_u64 v[108:109], s[18:19], 0, v[108:109]
	global_load_dwordx4 v[44:47], v[108:109], off
	global_load_dwordx4 v[48:51], v[108:109], off offset:16
	global_load_dwordx4 v[52:55], v[108:109], off offset:32
	global_load_dwordx4 v[56:59], v[108:109], off offset:48
	s_add_i32 s98, s98, 2
	v_lshlrev_b32_e32 v112, 2, v128
	v_add_u32_e32 v112, 0x20000, v112
	s_waitcnt vmcnt(8)
	v_pk_add_f32 v[114:115], v[14:15], v[18:19]
	v_pk_add_f32 v[116:117], v[12:13], v[16:17]
	v_pk_add_f32 v[118:119], v[22:23], v[26:27]
	v_pk_add_f32 v[120:121], v[20:21], v[24:25]
	v_pk_add_f32 v[114:115], v[114:115], v[118:119]
	v_pk_add_f32 v[116:117], v[116:117], v[120:121]
	v_add_f32_e32 v116, v117, v116
	v_add_f32_e32 v114, v114, v115
	v_add_f32_e32 v114, v116, v114
	v_fmamk_f32 v114, v114, 0x3a800000, v111
	v_rsq_f32_e32 v114, v114
	ds_write_b32 v112, v114
	s_waitcnt vmcnt(4)
	v_pk_add_f32 v[114:115], v[30:31], v[34:35]
	v_pk_add_f32 v[116:117], v[28:29], v[32:33]
	v_pk_add_f32 v[118:119], v[38:39], v[42:43]
	v_pk_add_f32 v[120:121], v[36:37], v[40:41]
	v_pk_add_f32 v[114:115], v[114:115], v[118:119]
	v_pk_add_f32 v[116:117], v[116:117], v[120:121]
	v_add_f32_e32 v116, v117, v116
	v_add_f32_e32 v114, v114, v115
	v_add_f32_e32 v114, v116, v114
	v_fmamk_f32 v114, v114, 0x3a800000, v111
	v_rsq_f32_e32 v114, v114
	ds_write_b32 v112, v114 offset:2048
	s_waitcnt vmcnt(0)
	v_pk_add_f32 v[114:115], v[46:47], v[50:51]
	v_pk_add_f32 v[116:117], v[44:45], v[48:49]
	v_pk_add_f32 v[118:119], v[54:55], v[58:59]
	v_pk_add_f32 v[120:121], v[52:53], v[56:57]
	v_pk_add_f32 v[114:115], v[114:115], v[118:119]
	v_pk_add_f32 v[116:117], v[116:117], v[120:121]
	v_add_f32_e32 v116, v117, v116
	v_add_f32_e32 v114, v114, v115
	v_add_f32_e32 v114, v116, v114
	v_fmamk_f32 v114, v114, 0x3a800000, v111
	v_rsq_f32_e32 v114, v114
	ds_write_b32 v112, v114 offset:4096

.LBB0_462:
	s_cmp_lt_i32 s74, 6
	s_cselect_b64 s[0:1], -1, 0
	s_cmp_gt_i32 s75, 5
	s_cselect_b64 s[4:5], -1, 0
	s_and_b64 s[0:1], s[0:1], s[4:5]
	s_andn2_b64 vcc, exec, s[0:1]
	s_cbranch_vccnz .LBB0_537
	v_lshlrev_b32_e32 v8, 2, v128
	s_ashr_i32 s3, s2, 31
	v_add_u32_e32 v0, 0, v8
	s_ashr_i32 s52, s72, 31
	s_mov_b32 s53, s72
	v_and_b32_e32 v4, 0xff, v128
	v_add_u32_e32 v5, 0xfffffe00, v128
	v_add_u32_e32 v6, 0x20000, v0
	v_lshrrev_b32_e32 v7, 8, v128
	s_mov_b64 s[0:1], 0
	s_waitcnt lgkmcnt(0)
	v_mov_b64_e32 v[0:1], s[2:3]
	s_mov_b64 s[4:5], 0xb00
	s_mov_b32 s10, 0x2e8ba2e9
	s_movk_i32 s11, 0xb0
	v_mov_b32_e32 v9, 0x358637bd
	s_movk_i32 s12, 0x8ff
	v_mov_b32_e32 v10, 0x160
	v_mov_b32_e32 v11, 0x161
	v_and_b32_e32 v110, 0xff, v128
	s_lshr_b32 s98, s91, 2
	v_mov_b32_e32 v111, 0x358637bd
	s_mul_i32 s99, s98, s72
	s_add_i32 s99, s99, s2
	s_cmp_lt_u32 s99, 0xb00
	s_cselect_b32 s99, s99, s2
	s_and_b32 s100, s99, 7
	s_mul_i32 s100, s100, 0x160
	s_lshr_b32 s101, s99, 3
	s_add_i32 s100, s100, s101
	s_mul_hi_u32 s101, s100, 0x1745d18
	s_lshl_b32 s101, s101, 3
	s_and_b32 s100, s100, 7
	s_or_b32 s101, s101, s100
	s_lshl_b32 s101, s101, 8
	v_add_u32_e32 v108, s101, v110
	v_lshlrev_b32_e32 v108, 6, v108
	v_mov_b32_e32 v109, 0
	v_lshl_add_u64 v[108:109], s[18:19], 0, v[108:109]
	global_load_dwordx4 v[12:15], v[108:109], off
	global_load_dwordx4 v[16:19], v[108:109], off offset:16
	global_load_dwordx4 v[20:23], v[108:109], off offset:32
	global_load_dwordx4 v[24:27], v[108:109], off offset:48
	s_add_i32 s98, s98, 2
	s_mul_i32 s99, s98, s72
	s_add_i32 s99, s99, s2
	s_cmp_lt_u32 s99, 0xb00
	s_cselect_b32 s99, s99, s2
	s_and_b32 s100, s99, 7
	s_mul_i32 s100, s100, 0x160
	s_lshr_b32 s101, s99, 3
	s_add_i32 s100, s100, s101
	s_mul_hi_u32 s101, s100, 0x1745d18
	s_lshl_b32 s101, s101, 3
	s_and_b32 s100, s100, 7
	s_or_b32 s101, s101, s100
	s_lshl_b32 s101, s101, 8
	v_add_u32_e32 v108, s101, v110
	v_lshlrev_b32_e32 v108, 6, v108
	v_mov_b32_e32 v109, 0
	v_lshl_add_u64 v[108:109], s[18:19], 0, v[108:109]
	global_load_dwordx4 v[28:31], v[108:109], off
	global_load_dwordx4 v[32:35], v[108:109], off offset:16
	global_load_dwordx4 v[36:39], v[108:109], off offset:32
	global_load_dwordx4 v[40:43], v[108:109], off offset:48
	s_add_i32 s98, s98, 2
	s_mul_i32 s99, s98, s72
	s_add_i32 s99, s99, s2
	s_cmp_lt_u32 s99, 0xb00
	s_cselect_b32 s99, s99, s2
	s_and_b32 s100, s99, 7
	s_mul_i32 s100, s100, 0x160
	s_lshr_b32 s101, s99, 3
	s_add_i32 s100, s100, s101
	s_mul_hi_u32 s101, s100, 0x1745d18
	s_lshl_b32 s101, s101, 3
	s_and_b32 s100, s100, 7
	s_or_b32 s101, s101, s100
	s_lshl_b32 s101, s101, 8
	v_add_u32_e32 v108, s101, v110
	v_lshlrev_b32_e32 v108, 6, v108
	v_mov_b32_e32 v109, 0
	v_lshl_add_u64 v[108:109], s[18:19], 0, v[108:109]
	global_load_dwordx4 v[44:47], v[108:109], off
	global_load_dwordx4 v[48:51], v[108:109], off offset:16
	global_load_dwordx4 v[52:55], v[108:109], off offset:32
	global_load_dwordx4 v[56:59], v[108:109], off offset:48
	s_add_i32 s98, s98, 2
	s_mul_i32 s99, s98, s72
	s_add_i32 s99, s99, s2
	s_cmp_lt_u32 s99, 0xb00
	s_cselect_b32 s99, s99, s2
	s_and_b32 s100, s99, 7
	s_mul_i32 s100, s100, 0x160
	s_lshr_b32 s101, s99, 3
	s_add_i32 s100, s100, s101
	s_mul_hi_u32 s101, s100, 0x1745d18
	s_lshl_b32 s101, s101, 3
	s_and_b32 s100, s100, 7
	s_or_b32 s101, s101, s100
	s_lshl_b32 s101, s101, 8
	v_add_u32_e32 v108, s101, v110
	v_lshlrev_b32_e32 v108, 6, v108
	v_mov_b32_e32 v109, 0
	v_lshl_add_u64 v[108:109], s[18:19], 0, v[108:109]
	global_load_dwordx4 v[60:63], v[108:109], off
	global_load_dwordx4 v[64:67], v[108:109], off offset:16
	global_load_dwordx4 v[68:71], v[108:109], off offset:32
	global_load_dwordx4 v[72:75], v[108:109], off offset:48
	s_add_i32 s98, s98, 2
	s_mul_i32 s99, s98, s72
	s_add_i32 s99, s99, s2
	s_cmp_lt_u32 s99, 0xb00
	s_cselect_b32 s99, s99, s2
	s_and_b32 s100, s99, 7
	s_mul_i32 s100, s100, 0x160
	s_lshr_b32 s101, s99, 3
	s_add_i32 s100, s100, s101
	s_mul_hi_u32 s101, s100, 0x1745d18
	s_lshl_b32 s101, s101, 3
	s_and_b32 s100, s100, 7
	s_or_b32 s101, s101, s100
	s_lshl_b32 s101, s101, 8
	v_add_u32_e32 v108, s101, v110
	v_lshlrev_b32_e32 v108, 6, v108
	v_mov_b32_e32 v109, 0
	v_lshl_add_u64 v[108:109], s[18:19], 0, v[108:109]
	global_load_dwordx4 v[76:79], v[108:109], off
	global_load_dwordx4 v[80:83], v[108:109], off offset:16
	global_load_dwordx4 v[84:87], v[108:109], off offset:32
	global_load_dwordx4 v[88:91], v[108:109], off offset:48
	s_add_i32 s98, s98, 2
	s_mul_i32 s99, s98, s72
	s_add_i32 s99, s99, s2
	s_cmp_lt_u32 s99, 0xb00
	s_cselect_b32 s99, s99, s2
	s_and_b32 s100, s99, 7
	s_mul_i32 s100, s100, 0x160
	s_lshr_b32 s101, s99, 3
	s_add_i32 s100, s100, s101
	s_mul_hi_u32 s101, s100, 0x1745d18
	s_lshl_b32 s101, s101, 3
	s_and_b32 s100, s100, 7
	s_or_b32 s101, s101, s100
	s_lshl_b32 s101, s101, 8
	v_add_u32_e32 v108, s101, v110
	v_lshlrev_b32_e32 v108, 6, v108
	v_mov_b32_e32 v109, 0
	v_lshl_add_u64 v[108:109], s[18:19], 0, v[108:109]
	global_load_dwordx4 v[92:95], v[108:109], off
	global_load_dwordx4 v[96:99], v[108:109], off offset:16
	global_load_dwordx4 v[100:103], v[108:109], off offset:32
	global_load_dwordx4 v[104:107], v[108:109], off offset:48
	s_add_i32 s98, s98, 2
	v_lshlrev_b32_e32 v112, 2, v128
	v_add_u32_e32 v112, 0x20000, v112
	s_waitcnt vmcnt(20)
	v_pk_add_f32 v[114:115], v[14:15], v[18:19]
	v_pk_add_f32 v[116:117], v[12:13], v[16:17]
	v_pk_add_f32 v[118:119], v[22:23], v[26:27]
	v_pk_add_f32 v[120:121], v[20:21], v[24:25]
	v_pk_add_f32 v[114:115], v[114:115], v[118:119]
	v_pk_add_f32 v[116:117], v[116:117], v[120:121]
	v_add_f32_e32 v116, v117, v116
	v_add_f32_e32 v114, v114, v115
	v_add_f32_e32 v114, v116, v114
	v_fmamk_f32 v114, v114, 0x3a800000, v111
	v_rsq_f32_e32 v114, v114
	ds_write_b32 v112, v114
	s_waitcnt vmcnt(16)
	v_pk_add_f32 v[114:115], v[30:31], v[34:35]
	v_pk_add_f32 v[116:117], v[28:29], v[32:33]
	v_pk_add_f32 v[118:119], v[38:39], v[42:43]
	v_pk_add_f32 v[120:121], v[36:37], v[40:41]
	v_pk_add_f32 v[114:115], v[114:115], v[118:119]
	v_pk_add_f32 v[116:117], v[116:117], v[120:121]
	v_add_f32_e32 v116, v117, v116
	v_add_f32_e32 v114, v114, v115
	v_add_f32_e32 v114, v116, v114
	v_fmamk_f32 v114, v114, 0x3a800000, v111
	v_rsq_f32_e32 v114, v114
	ds_write_b32 v112, v114 offset:2048
	s_waitcnt vmcnt(12)
	v_pk_add_f32 v[114:115], v[46:47], v[50:51]
	v_pk_add_f32 v[116:117], v[44:45], v[48:49]
	v_pk_add_f32 v[118:119], v[54:55], v[58:59]
	v_pk_add_f32 v[120:121], v[52:53], v[56:57]
	v_pk_add_f32 v[114:115], v[114:115], v[118:119]
	v_pk_add_f32 v[116:117], v[116:117], v[120:121]
	v_add_f32_e32 v116, v117, v116
	v_add_f32_e32 v114, v114, v115
	v_add_f32_e32 v114, v116, v114
	v_fmamk_f32 v114, v114, 0x3a800000, v111
	v_rsq_f32_e32 v114, v114
	ds_write_b32 v112, v114 offset:4096
	s_waitcnt vmcnt(8)
	v_pk_add_f32 v[114:115], v[62:63], v[66:67]
	v_pk_add_f32 v[116:117], v[60:61], v[64:65]
	v_pk_add_f32 v[118:119], v[70:71], v[74:75]
	v_pk_add_f32 v[120:121], v[68:69], v[72:73]
	v_pk_add_f32 v[114:115], v[114:115], v[118:119]
	v_pk_add_f32 v[116:117], v[116:117], v[120:121]
	v_add_f32_e32 v116, v117, v116
	v_add_f32_e32 v114, v114, v115
	v_add_f32_e32 v114, v116, v114
	v_fmamk_f32 v114, v114, 0x3a800000, v111
	v_rsq_f32_e32 v114, v114
	ds_write_b32 v112, v114 offset:6144
	s_waitcnt vmcnt(4)
	v_pk_add_f32 v[114:115], v[78:79], v[82:83]
	v_pk_add_f32 v[116:117], v[76:77], v[80:81]
	v_pk_add_f32 v[118:119], v[86:87], v[90:91]
	v_pk_add_f32 v[120:121], v[84:85], v[88:89]
	v_pk_add_f32 v[114:115], v[114:115], v[118:119]
	v_pk_add_f32 v[116:117], v[116:117], v[120:121]
	v_add_f32_e32 v116, v117, v116
	v_add_f32_e32 v114, v114, v115
	v_add_f32_e32 v114, v116, v114
	v_fmamk_f32 v114, v114, 0x3a800000, v111
	v_rsq_f32_e32 v114, v114
	ds_write_b32 v112, v114 offset:8192
	s_waitcnt vmcnt(0)
	v_pk_add_f32 v[114:115], v[94:95], v[98:99]
	v_pk_add_f32 v[116:117], v[92:93], v[96:97]
	v_pk_add_f32 v[118:119], v[102:103], v[106:107]
	v_pk_add_f32 v[120:121], v[100:101], v[104:105]
	v_pk_add_f32 v[114:115], v[114:115], v[118:119]
	v_pk_add_f32 v[116:117], v[116:117], v[120:121]
	v_add_f32_e32 v116, v117, v116
	v_add_f32_e32 v114, v114, v115
	v_add_f32_e32 v114, v116, v114
	v_fmamk_f32 v114, v114, 0x3a800000, v111
	v_rsq_f32_e32 v114, v114
	ds_write_b32 v112, v114 offset:10240

.LBB0_638:
	s_cmp_lt_i32 s74, 8
	s_cselect_b64 s[0:1], -1, 0
	s_cmp_gt_i32 s75, 7
	s_cselect_b64 s[4:5], -1, 0
	s_and_b64 s[0:1], s[0:1], s[4:5]
	s_andn2_b64 vcc, exec, s[0:1]
	s_cbranch_vccnz .LBB0_779
	v_lshlrev_b32_e32 v8, 2, v128
	s_ashr_i32 s3, s2, 31
	v_add_u32_e32 v0, 0, v8
	s_ashr_i32 s58, s72, 31
	s_mov_b32 s59, s72
	v_and_b32_e32 v4, 0xff, v128
	v_add_u32_e32 v5, 0xfffffe00, v128
	v_add_u32_e32 v6, 0x20000, v0
	v_lshrrev_b32_e32 v7, 8, v128
	s_mov_b64 s[0:1], 0
	s_waitcnt lgkmcnt(0)
	v_mov_b64_e32 v[0:1], s[2:3]
	s_mov_b64 s[4:5], 0x600
	s_mov_b32 s10, 0x2aaaaaab
	s_movk_i32 s11, 0x60
	v_mov_b32_e32 v9, 0x358637bd
	s_movk_i32 s12, 0x8ff
	v_mov_b32_e32 v10, 0xc0
	v_mov_b32_e32 v11, 0xc1
	v_and_b32_e32 v110, 0xff, v128
	s_lshr_b32 s98, s91, 2
	v_mov_b32_e32 v111, 0x358637bd
	s_mul_i32 s99, s98, s72
	s_add_i32 s99, s99, s2
	s_cmp_lt_u32 s99, 0x600
	s_cselect_b32 s99, s99, s2
	s_and_b32 s100, s99, 7
	s_mul_i32 s100, s100, 0xc0
	s_lshr_b32 s101, s99, 3
	s_add_i32 s100, s100, s101
	s_mul_hi_u32 s101, s100, 0x2aaaaab
	s_lshl_b32 s101, s101, 3
	s_and_b32 s100, s100, 7
	s_or_b32 s101, s101, s100
	s_lshl_b32 s101, s101, 8
	v_add_u32_e32 v108, s101, v110
	v_lshlrev_b32_e32 v108, 6, v108
	v_mov_b32_e32 v109, 0
	v_lshl_add_u64 v[108:109], s[18:19], 0, v[108:109]
	global_load_dwordx4 v[12:15], v[108:109], off
	global_load_dwordx4 v[16:19], v[108:109], off offset:16
	global_load_dwordx4 v[20:23], v[108:109], off offset:32
	global_load_dwordx4 v[24:27], v[108:109], off offset:48
	s_add_i32 s98, s98, 2
	s_mul_i32 s99, s98, s72
	s_add_i32 s99, s99, s2
	s_cmp_lt_u32 s99, 0x600
	s_cselect_b32 s99, s99, s2
	s_and_b32 s100, s99, 7
	s_mul_i32 s100, s100, 0xc0
	s_lshr_b32 s101, s99, 3
	s_add_i32 s100, s100, s101
	s_mul_hi_u32 s101, s100, 0x2aaaaab
	s_lshl_b32 s101, s101, 3
	s_and_b32 s100, s100, 7
	s_or_b32 s101, s101, s100
	s_lshl_b32 s101, s101, 8
	v_add_u32_e32 v108, s101, v110
	v_lshlrev_b32_e32 v108, 6, v108
	v_mov_b32_e32 v109, 0
	v_lshl_add_u64 v[108:109], s[18:19], 0, v[108:109]
	global_load_dwordx4 v[28:31], v[108:109], off
	global_load_dwordx4 v[32:35], v[108:109], off offset:16
	global_load_dwordx4 v[36:39], v[108:109], off offset:32
	global_load_dwordx4 v[40:43], v[108:109], off offset:48
	s_add_i32 s98, s98, 2
	s_mul_i32 s99, s98, s72
	s_add_i32 s99, s99, s2
	s_cmp_lt_u32 s99, 0x600
	s_cselect_b32 s99, s99, s2
	s_and_b32 s100, s99, 7
	s_mul_i32 s100, s100, 0xc0
	s_lshr_b32 s101, s99, 3
	s_add_i32 s100, s100, s101
	s_mul_hi_u32 s101, s100, 0x2aaaaab
	s_lshl_b32 s101, s101, 3
	s_and_b32 s100, s100, 7
	s_or_b32 s101, s101, s100
	s_lshl_b32 s101, s101, 8
	v_add_u32_e32 v108, s101, v110
	v_lshlrev_b32_e32 v108, 6, v108
	v_mov_b32_e32 v109, 0
	v_lshl_add_u64 v[108:109], s[18:19], 0, v[108:109]
	global_load_dwordx4 v[44:47], v[108:109], off
	global_load_dwordx4 v[48:51], v[108:109], off offset:16
	global_load_dwordx4 v[52:55], v[108:109], off offset:32
	global_load_dwordx4 v[56:59], v[108:109], off offset:48
	s_add_i32 s98, s98, 2
	v_lshlrev_b32_e32 v112, 2, v128
	v_add_u32_e32 v112, 0x20000, v112
	s_waitcnt vmcnt(8)
	v_pk_add_f32 v[114:115], v[14:15], v[18:19]
	v_pk_add_f32 v[116:117], v[12:13], v[16:17]
	v_pk_add_f32 v[118:119], v[22:23], v[26:27]
	v_pk_add_f32 v[120:121], v[20:21], v[24:25]
	v_pk_add_f32 v[114:115], v[114:115], v[118:119]
	v_pk_add_f32 v[116:117], v[116:117], v[120:121]
	v_add_f32_e32 v116, v117, v116
	v_add_f32_e32 v114, v114, v115
	v_add_f32_e32 v114, v116, v114
	v_fmamk_f32 v114, v114, 0x3a800000, v111
	v_rsq_f32_e32 v114, v114
	ds_write_b32 v112, v114
	s_waitcnt vmcnt(4)
	v_pk_add_f32 v[114:115], v[30:31], v[34:35]
	v_pk_add_f32 v[116:117], v[28:29], v[32:33]
	v_pk_add_f32 v[118:119], v[38:39], v[42:43]
	v_pk_add_f32 v[120:121], v[36:37], v[40:41]
	v_pk_add_f32 v[114:115], v[114:115], v[118:119]
	v_pk_add_f32 v[116:117], v[116:117], v[120:121]
	v_add_f32_e32 v116, v117, v116
	v_add_f32_e32 v114, v114, v115
	v_add_f32_e32 v114, v116, v114
	v_fmamk_f32 v114, v114, 0x3a800000, v111
	v_rsq_f32_e32 v114, v114
	ds_write_b32 v112, v114 offset:2048
	s_waitcnt vmcnt(0)
	v_pk_add_f32 v[114:115], v[46:47], v[50:51]
	v_pk_add_f32 v[116:117], v[44:45], v[48:49]
	v_pk_add_f32 v[118:119], v[54:55], v[58:59]
	v_pk_add_f32 v[120:121], v[52:53], v[56:57]
	v_pk_add_f32 v[114:115], v[114:115], v[118:119]
	v_pk_add_f32 v[116:117], v[116:117], v[120:121]
	v_add_f32_e32 v116, v117, v116
	v_add_f32_e32 v114, v114, v115
	v_add_f32_e32 v114, v116, v114
	v_fmamk_f32 v114, v114, 0x3a800000, v111
	v_rsq_f32_e32 v114, v114
	ds_write_b32 v112, v114 offset:4096

.LBB0_1045:
	s_cmp_lt_i32 s74, 11
	s_cselect_b64 s[0:1], -1, 0
	s_cmp_gt_i32 s75, 10
	s_cselect_b64 s[4:5], -1, 0
	s_and_b64 s[0:1], s[0:1], s[4:5]
	s_andn2_b64 vcc, exec, s[0:1]
	s_cbranch_vccnz .LBB0_1120
	v_lshlrev_b32_e32 v8, 2, v128
	s_ashr_i32 s3, s2, 31
	s_waitcnt vmcnt(0)
	v_add_u32_e32 v0, 0, v8
	s_ashr_i32 s42, s72, 31
	s_mov_b32 s43, s72
	v_and_b32_e32 v4, 0xff, v128
	v_add_u32_e32 v5, 0xfffffe00, v128
	v_add_u32_e32 v6, 0x20000, v0
	v_lshrrev_b32_e32 v7, 8, v128
	s_mov_b64 s[0:1], 0
	s_waitcnt lgkmcnt(0)
	v_mov_b64_e32 v[0:1], s[2:3]
	s_mov_b64 s[4:5], 0xb00
	s_mov_b32 s10, 0x2e8ba2e9
	s_movk_i32 s11, 0xb0
	v_mov_b32_e32 v9, 0x358637bd
	s_movk_i32 s12, 0x8ff
	v_mov_b32_e32 v10, 0x160
	v_mov_b32_e32 v11, 0x161
	v_and_b32_e32 v110, 0xff, v128
	s_lshr_b32 s98, s91, 2
	v_mov_b32_e32 v111, 0x358637bd
	s_mul_i32 s99, s98, s72
	s_add_i32 s99, s99, s2
	s_cmp_lt_u32 s99, 0xb00
	s_cselect_b32 s99, s99, s2
	s_and_b32 s100, s99, 7
	s_mul_i32 s100, s100, 0x160
	s_lshr_b32 s101, s99, 3
	s_add_i32 s100, s100, s101
	s_mul_hi_u32 s101, s100, 0x1745d18
	s_lshl_b32 s101, s101, 3
	s_and_b32 s100, s100, 7
	s_or_b32 s101, s101, s100
	s_lshl_b32 s101, s101, 8
	v_add_u32_e32 v108, s101, v110
	v_lshlrev_b32_e32 v108, 6, v108
	v_mov_b32_e32 v109, 0
	v_lshl_add_u64 v[108:109], s[18:19], 0, v[108:109]
	global_load_dwordx4 v[12:15], v[108:109], off
	global_load_dwordx4 v[16:19], v[108:109], off offset:16
	global_load_dwordx4 v[20:23], v[108:109], off offset:32
	global_load_dwordx4 v[24:27], v[108:109], off offset:48
	s_add_i32 s98, s98, 2
	s_mul_i32 s99, s98, s72
	s_add_i32 s99, s99, s2
	s_cmp_lt_u32 s99, 0xb00
	s_cselect_b32 s99, s99, s2
	s_and_b32 s100, s99, 7
	s_mul_i32 s100, s100, 0x160
	s_lshr_b32 s101, s99, 3
	s_add_i32 s100, s100, s101
	s_mul_hi_u32 s101, s100, 0x1745d18
	s_lshl_b32 s101, s101, 3
	s_and_b32 s100, s100, 7
	s_or_b32 s101, s101, s100
	s_lshl_b32 s101, s101, 8
	v_add_u32_e32 v108, s101, v110
	v_lshlrev_b32_e32 v108, 6, v108
	v_mov_b32_e32 v109, 0
	v_lshl_add_u64 v[108:109], s[18:19], 0, v[108:109]
	global_load_dwordx4 v[28:31], v[108:109], off
	global_load_dwordx4 v[32:35], v[108:109], off offset:16
	global_load_dwordx4 v[36:39], v[108:109], off offset:32
	global_load_dwordx4 v[40:43], v[108:109], off offset:48
	s_add_i32 s98, s98, 2
	s_mul_i32 s99, s98, s72
	s_add_i32 s99, s99, s2
	s_cmp_lt_u32 s99, 0xb00
	s_cselect_b32 s99, s99, s2
	s_and_b32 s100, s99, 7
	s_mul_i32 s100, s100, 0x160
	s_lshr_b32 s101, s99, 3
	s_add_i32 s100, s100, s101
	s_mul_hi_u32 s101, s100, 0x1745d18
	s_lshl_b32 s101, s101, 3
	s_and_b32 s100, s100, 7
	s_or_b32 s101, s101, s100
	s_lshl_b32 s101, s101, 8
	v_add_u32_e32 v108, s101, v110
	v_lshlrev_b32_e32 v108, 6, v108
	v_mov_b32_e32 v109, 0
	v_lshl_add_u64 v[108:109], s[18:19], 0, v[108:109]
	global_load_dwordx4 v[44:47], v[108:109], off
	global_load_dwordx4 v[48:51], v[108:109], off offset:16
	global_load_dwordx4 v[52:55], v[108:109], off offset:32
	global_load_dwordx4 v[56:59], v[108:109], off offset:48
	s_add_i32 s98, s98, 2
	s_mul_i32 s99, s98, s72
	s_add_i32 s99, s99, s2
	s_cmp_lt_u32 s99, 0xb00
	s_cselect_b32 s99, s99, s2
	s_and_b32 s100, s99, 7
	s_mul_i32 s100, s100, 0x160
	s_lshr_b32 s101, s99, 3
	s_add_i32 s100, s100, s101
	s_mul_hi_u32 s101, s100, 0x1745d18
	s_lshl_b32 s101, s101, 3
	s_and_b32 s100, s100, 7
	s_or_b32 s101, s101, s100
	s_lshl_b32 s101, s101, 8
	v_add_u32_e32 v108, s101, v110
	v_lshlrev_b32_e32 v108, 6, v108
	v_mov_b32_e32 v109, 0
	v_lshl_add_u64 v[108:109], s[18:19], 0, v[108:109]
	global_load_dwordx4 v[60:63], v[108:109], off
	global_load_dwordx4 v[64:67], v[108:109], off offset:16
	global_load_dwordx4 v[68:71], v[108:109], off offset:32
	global_load_dwordx4 v[72:75], v[108:109], off offset:48
	s_add_i32 s98, s98, 2
	s_mul_i32 s99, s98, s72
	s_add_i32 s99, s99, s2
	s_cmp_lt_u32 s99, 0xb00
	s_cselect_b32 s99, s99, s2
	s_and_b32 s100, s99, 7
	s_mul_i32 s100, s100, 0x160
	s_lshr_b32 s101, s99, 3
	s_add_i32 s100, s100, s101
	s_mul_hi_u32 s101, s100, 0x1745d18
	s_lshl_b32 s101, s101, 3
	s_and_b32 s100, s100, 7
	s_or_b32 s101, s101, s100
	s_lshl_b32 s101, s101, 8
	v_add_u32_e32 v108, s101, v110
	v_lshlrev_b32_e32 v108, 6, v108
	v_mov_b32_e32 v109, 0
	v_lshl_add_u64 v[108:109], s[18:19], 0, v[108:109]
	global_load_dwordx4 v[76:79], v[108:109], off
	global_load_dwordx4 v[80:83], v[108:109], off offset:16
	global_load_dwordx4 v[84:87], v[108:109], off offset:32
	global_load_dwordx4 v[88:91], v[108:109], off offset:48
	s_add_i32 s98, s98, 2
	s_mul_i32 s99, s98, s72
	s_add_i32 s99, s99, s2
	s_cmp_lt_u32 s99, 0xb00
	s_cselect_b32 s99, s99, s2
	s_and_b32 s100, s99, 7
	s_mul_i32 s100, s100, 0x160
	s_lshr_b32 s101, s99, 3
	s_add_i32 s100, s100, s101
	s_mul_hi_u32 s101, s100, 0x1745d18
	s_lshl_b32 s101, s101, 3
	s_and_b32 s100, s100, 7
	s_or_b32 s101, s101, s100
	s_lshl_b32 s101, s101, 8
	v_add_u32_e32 v108, s101, v110
	v_lshlrev_b32_e32 v108, 6, v108
	v_mov_b32_e32 v109, 0
	v_lshl_add_u64 v[108:109], s[18:19], 0, v[108:109]
	global_load_dwordx4 v[92:95], v[108:109], off
	global_load_dwordx4 v[96:99], v[108:109], off offset:16
	global_load_dwordx4 v[100:103], v[108:109], off offset:32
	global_load_dwordx4 v[104:107], v[108:109], off offset:48
	s_add_i32 s98, s98, 2
	v_lshlrev_b32_e32 v112, 2, v128
	v_add_u32_e32 v112, 0x20000, v112
	s_waitcnt vmcnt(20)
	v_pk_add_f32 v[114:115], v[14:15], v[18:19]
	v_pk_add_f32 v[116:117], v[12:13], v[16:17]
	v_pk_add_f32 v[118:119], v[22:23], v[26:27]
	v_pk_add_f32 v[120:121], v[20:21], v[24:25]
	v_pk_add_f32 v[114:115], v[114:115], v[118:119]
	v_pk_add_f32 v[116:117], v[116:117], v[120:121]
	v_add_f32_e32 v116, v117, v116
	v_add_f32_e32 v114, v114, v115
	v_add_f32_e32 v114, v116, v114
	v_fmamk_f32 v114, v114, 0x3a800000, v111
	v_rsq_f32_e32 v114, v114
	ds_write_b32 v112, v114
	s_waitcnt vmcnt(16)
	v_pk_add_f32 v[114:115], v[30:31], v[34:35]
	v_pk_add_f32 v[116:117], v[28:29], v[32:33]
	v_pk_add_f32 v[118:119], v[38:39], v[42:43]
	v_pk_add_f32 v[120:121], v[36:37], v[40:41]
	v_pk_add_f32 v[114:115], v[114:115], v[118:119]
	v_pk_add_f32 v[116:117], v[116:117], v[120:121]
	v_add_f32_e32 v116, v117, v116
	v_add_f32_e32 v114, v114, v115
	v_add_f32_e32 v114, v116, v114
	v_fmamk_f32 v114, v114, 0x3a800000, v111
	v_rsq_f32_e32 v114, v114
	ds_write_b32 v112, v114 offset:2048
	s_waitcnt vmcnt(12)
	v_pk_add_f32 v[114:115], v[46:47], v[50:51]
	v_pk_add_f32 v[116:117], v[44:45], v[48:49]
	v_pk_add_f32 v[118:119], v[54:55], v[58:59]
	v_pk_add_f32 v[120:121], v[52:53], v[56:57]
	v_pk_add_f32 v[114:115], v[114:115], v[118:119]
	v_pk_add_f32 v[116:117], v[116:117], v[120:121]
	v_add_f32_e32 v116, v117, v116
	v_add_f32_e32 v114, v114, v115
	v_add_f32_e32 v114, v116, v114
	v_fmamk_f32 v114, v114, 0x3a800000, v111
	v_rsq_f32_e32 v114, v114
	ds_write_b32 v112, v114 offset:4096
	s_waitcnt vmcnt(8)
	v_pk_add_f32 v[114:115], v[62:63], v[66:67]
	v_pk_add_f32 v[116:117], v[60:61], v[64:65]
	v_pk_add_f32 v[118:119], v[70:71], v[74:75]
	v_pk_add_f32 v[120:121], v[68:69], v[72:73]
	v_pk_add_f32 v[114:115], v[114:115], v[118:119]
	v_pk_add_f32 v[116:117], v[116:117], v[120:121]
	v_add_f32_e32 v116, v117, v116
	v_add_f32_e32 v114, v114, v115
	v_add_f32_e32 v114, v116, v114
	v_fmamk_f32 v114, v114, 0x3a800000, v111
	v_rsq_f32_e32 v114, v114
	ds_write_b32 v112, v114 offset:6144
	s_waitcnt vmcnt(4)
	v_pk_add_f32 v[114:115], v[78:79], v[82:83]
	v_pk_add_f32 v[116:117], v[76:77], v[80:81]
	v_pk_add_f32 v[118:119], v[86:87], v[90:91]
	v_pk_add_f32 v[120:121], v[84:85], v[88:89]
	v_pk_add_f32 v[114:115], v[114:115], v[118:119]
	v_pk_add_f32 v[116:117], v[116:117], v[120:121]
	v_add_f32_e32 v116, v117, v116
	v_add_f32_e32 v114, v114, v115
	v_add_f32_e32 v114, v116, v114
	v_fmamk_f32 v114, v114, 0x3a800000, v111
	v_rsq_f32_e32 v114, v114
	ds_write_b32 v112, v114 offset:8192
	s_waitcnt vmcnt(0)
	v_pk_add_f32 v[114:115], v[94:95], v[98:99]
	v_pk_add_f32 v[116:117], v[92:93], v[96:97]
	v_pk_add_f32 v[118:119], v[102:103], v[106:107]
	v_pk_add_f32 v[120:121], v[100:101], v[104:105]
	v_pk_add_f32 v[114:115], v[114:115], v[118:119]
	v_pk_add_f32 v[116:117], v[116:117], v[120:121]
	v_add_f32_e32 v116, v117, v116
	v_add_f32_e32 v114, v114, v115
	v_add_f32_e32 v114, v116, v114
	v_fmamk_f32 v114, v114, 0x3a800000, v111
	v_rsq_f32_e32 v114, v114
	ds_write_b32 v112, v114 offset:10240

.LBB0_1221:
	s_cmp_lt_i32 s74, 13
	s_cselect_b64 s[0:1], -1, 0
	s_cmp_gt_i32 s75, 12
	s_cselect_b64 s[4:5], -1, 0
	s_and_b64 s[0:1], s[0:1], s[4:5]
	s_andn2_b64 vcc, exec, s[0:1]
	s_cbranch_vccnz .LBB0_1296
	v_lshlrev_b32_e32 v8, 2, v128
	s_ashr_i32 s3, s2, 31
	s_waitcnt vmcnt(0)
	v_add_u32_e32 v0, 0, v8
	s_ashr_i32 s42, s72, 31
	s_mov_b32 s43, s72
	v_and_b32_e32 v4, 0xff, v128
	v_add_u32_e32 v5, 0xfffffe00, v128
	v_add_u32_e32 v6, 0x20000, v0
	v_lshrrev_b32_e32 v7, 8, v128
	s_mov_b64 s[0:1], 0
	s_waitcnt lgkmcnt(0)
	v_mov_b64_e32 v[0:1], s[2:3]
	s_mov_b64 s[4:5], 0x600
	s_mov_b32 s10, 0x2aaaaaab
	s_movk_i32 s11, 0x60
	v_mov_b32_e32 v9, 0x358637bd
	s_movk_i32 s12, 0x8ff
	v_mov_b32_e32 v10, 0xc0
	v_mov_b32_e32 v11, 0xc1
	v_and_b32_e32 v110, 0xff, v128
	s_lshr_b32 s98, s91, 2
	v_mov_b32_e32 v111, 0x358637bd
	s_mul_i32 s99, s98, s72
	s_add_i32 s99, s99, s2
	s_cmp_lt_u32 s99, 0x600
	s_cselect_b32 s99, s99, s2
	s_and_b32 s100, s99, 7
	s_mul_i32 s100, s100, 0xc0
	s_lshr_b32 s101, s99, 3
	s_add_i32 s100, s100, s101
	s_mul_hi_u32 s101, s100, 0x2aaaaab
	s_lshl_b32 s101, s101, 3
	s_and_b32 s100, s100, 7
	s_or_b32 s101, s101, s100
	s_lshl_b32 s101, s101, 8
	v_add_u32_e32 v108, s101, v110
	v_lshlrev_b32_e32 v108, 6, v108
	v_mov_b32_e32 v109, 0
	v_lshl_add_u64 v[108:109], s[18:19], 0, v[108:109]
	global_load_dwordx4 v[12:15], v[108:109], off
	global_load_dwordx4 v[16:19], v[108:109], off offset:16
	global_load_dwordx4 v[20:23], v[108:109], off offset:32
	global_load_dwordx4 v[24:27], v[108:109], off offset:48
	s_add_i32 s98, s98, 2
	s_mul_i32 s99, s98, s72
	s_add_i32 s99, s99, s2
	s_cmp_lt_u32 s99, 0x600
	s_cselect_b32 s99, s99, s2
	s_and_b32 s100, s99, 7
	s_mul_i32 s100, s100, 0xc0
	s_lshr_b32 s101, s99, 3
	s_add_i32 s100, s100, s101
	s_mul_hi_u32 s101, s100, 0x2aaaaab
	s_lshl_b32 s101, s101, 3
	s_and_b32 s100, s100, 7
	s_or_b32 s101, s101, s100
	s_lshl_b32 s101, s101, 8
	v_add_u32_e32 v108, s101, v110
	v_lshlrev_b32_e32 v108, 6, v108
	v_mov_b32_e32 v109, 0
	v_lshl_add_u64 v[108:109], s[18:19], 0, v[108:109]
	global_load_dwordx4 v[28:31], v[108:109], off
	global_load_dwordx4 v[32:35], v[108:109], off offset:16
	global_load_dwordx4 v[36:39], v[108:109], off offset:32
	global_load_dwordx4 v[40:43], v[108:109], off offset:48
	s_add_i32 s98, s98, 2
	s_mul_i32 s99, s98, s72
	s_add_i32 s99, s99, s2
	s_cmp_lt_u32 s99, 0x600
	s_cselect_b32 s99, s99, s2
	s_and_b32 s100, s99, 7
	s_mul_i32 s100, s100, 0xc0
	s_lshr_b32 s101, s99, 3
	s_add_i32 s100, s100, s101
	s_mul_hi_u32 s101, s100, 0x2aaaaab
	s_lshl_b32 s101, s101, 3
	s_and_b32 s100, s100, 7
	s_or_b32 s101, s101, s100
	s_lshl_b32 s101, s101, 8
	v_add_u32_e32 v108, s101, v110
	v_lshlrev_b32_e32 v108, 6, v108
	v_mov_b32_e32 v109, 0
	v_lshl_add_u64 v[108:109], s[18:19], 0, v[108:109]
	global_load_dwordx4 v[44:47], v[108:109], off
	global_load_dwordx4 v[48:51], v[108:109], off offset:16
	global_load_dwordx4 v[52:55], v[108:109], off offset:32
	global_load_dwordx4 v[56:59], v[108:109], off offset:48
	s_add_i32 s98, s98, 2
	v_lshlrev_b32_e32 v112, 2, v128
	v_add_u32_e32 v112, 0x20000, v112
	s_waitcnt vmcnt(8)
	v_pk_add_f32 v[114:115], v[14:15], v[18:19]
	v_pk_add_f32 v[116:117], v[12:13], v[16:17]
	v_pk_add_f32 v[118:119], v[22:23], v[26:27]
	v_pk_add_f32 v[120:121], v[20:21], v[24:25]
	v_pk_add_f32 v[114:115], v[114:115], v[118:119]
	v_pk_add_f32 v[116:117], v[116:117], v[120:121]
	v_add_f32_e32 v116, v117, v116
	v_add_f32_e32 v114, v114, v115
	v_add_f32_e32 v114, v116, v114
	v_fmamk_f32 v114, v114, 0x3a800000, v111
	v_rsq_f32_e32 v114, v114
	ds_write_b32 v112, v114
	s_waitcnt vmcnt(4)
	v_pk_add_f32 v[114:115], v[30:31], v[34:35]
	v_pk_add_f32 v[116:117], v[28:29], v[32:33]
	v_pk_add_f32 v[118:119], v[38:39], v[42:43]
	v_pk_add_f32 v[120:121], v[36:37], v[40:41]
	v_pk_add_f32 v[114:115], v[114:115], v[118:119]
	v_pk_add_f32 v[116:117], v[116:117], v[120:121]
	v_add_f32_e32 v116, v117, v116
	v_add_f32_e32 v114, v114, v115
	v_add_f32_e32 v114, v116, v114
	v_fmamk_f32 v114, v114, 0x3a800000, v111
	v_rsq_f32_e32 v114, v114
	ds_write_b32 v112, v114 offset:2048
	s_waitcnt vmcnt(0)
	v_pk_add_f32 v[114:115], v[46:47], v[50:51]
	v_pk_add_f32 v[116:117], v[44:45], v[48:49]
	v_pk_add_f32 v[118:119], v[54:55], v[58:59]
	v_pk_add_f32 v[120:121], v[52:53], v[56:57]
	v_pk_add_f32 v[114:115], v[114:115], v[118:119]
	v_pk_add_f32 v[116:117], v[116:117], v[120:121]
	v_add_f32_e32 v116, v117, v116
	v_add_f32_e32 v114, v114, v115
	v_add_f32_e32 v114, v116, v114
	v_fmamk_f32 v114, v114, 0x3a800000, v111
	v_rsq_f32_e32 v114, v114
	ds_write_b32 v112, v114 offset:4096

.LBB0_1633:
	s_cmp_lt_i32 s74, 18
	s_cselect_b64 s[0:1], -1, 0
	s_cmp_gt_i32 s75, 17
	s_cselect_b64 s[4:5], -1, 0
	s_and_b64 s[0:1], s[0:1], s[4:5]
	s_andn2_b64 vcc, exec, s[0:1]
	s_cbranch_vccnz .LBB0_1708
	s_waitcnt vmcnt(0)
	v_lshlrev_b32_e32 v8, 2, v128
	s_ashr_i32 s3, s2, 31
	v_add_u32_e32 v0, 0, v8
	s_ashr_i32 s42, s72, 31
	s_mov_b32 s43, s72
	v_and_b32_e32 v4, 0xff, v128
	v_add_u32_e32 v5, 0xfffffe00, v128
	v_add_u32_e32 v6, 0x20000, v0
	v_lshrrev_b32_e32 v7, 8, v128
	s_mov_b64 s[0:1], 0
	s_waitcnt lgkmcnt(0)
	v_mov_b64_e32 v[0:1], s[2:3]
	s_mov_b64 s[4:5], 0xb00
	s_mov_b32 s10, 0x2e8ba2e9
	s_movk_i32 s11, 0xb0
	v_mov_b32_e32 v9, 0x358637bd
	s_movk_i32 s12, 0x8ff
	v_mov_b32_e32 v10, 0x160
	v_mov_b32_e32 v11, 0x161
	v_and_b32_e32 v110, 0xff, v128
	s_lshr_b32 s98, s91, 2
	v_mov_b32_e32 v111, 0x358637bd
	s_mul_i32 s99, s98, s72
	s_add_i32 s99, s99, s2
	s_cmp_lt_u32 s99, 0xb00
	s_cselect_b32 s99, s99, s2
	s_and_b32 s100, s99, 7
	s_mul_i32 s100, s100, 0x160
	s_lshr_b32 s101, s99, 3
	s_add_i32 s100, s100, s101
	s_mul_hi_u32 s101, s100, 0x1745d18
	s_lshl_b32 s101, s101, 3
	s_and_b32 s100, s100, 7
	s_or_b32 s101, s101, s100
	s_lshl_b32 s101, s101, 8
	v_add_u32_e32 v108, s101, v110
	v_lshlrev_b32_e32 v108, 6, v108
	v_mov_b32_e32 v109, 0
	v_lshl_add_u64 v[108:109], s[18:19], 0, v[108:109]
	global_load_dwordx4 v[12:15], v[108:109], off
	global_load_dwordx4 v[16:19], v[108:109], off offset:16
	global_load_dwordx4 v[20:23], v[108:109], off offset:32
	global_load_dwordx4 v[24:27], v[108:109], off offset:48
	s_add_i32 s98, s98, 2
	s_mul_i32 s99, s98, s72
	s_add_i32 s99, s99, s2
	s_cmp_lt_u32 s99, 0xb00
	s_cselect_b32 s99, s99, s2
	s_and_b32 s100, s99, 7
	s_mul_i32 s100, s100, 0x160
	s_lshr_b32 s101, s99, 3
	s_add_i32 s100, s100, s101
	s_mul_hi_u32 s101, s100, 0x1745d18
	s_lshl_b32 s101, s101, 3
	s_and_b32 s100, s100, 7
	s_or_b32 s101, s101, s100
	s_lshl_b32 s101, s101, 8
	v_add_u32_e32 v108, s101, v110
	v_lshlrev_b32_e32 v108, 6, v108
	v_mov_b32_e32 v109, 0
	v_lshl_add_u64 v[108:109], s[18:19], 0, v[108:109]
	global_load_dwordx4 v[28:31], v[108:109], off
	global_load_dwordx4 v[32:35], v[108:109], off offset:16
	global_load_dwordx4 v[36:39], v[108:109], off offset:32
	global_load_dwordx4 v[40:43], v[108:109], off offset:48
	s_add_i32 s98, s98, 2
	s_mul_i32 s99, s98, s72
	s_add_i32 s99, s99, s2
	s_cmp_lt_u32 s99, 0xb00
	s_cselect_b32 s99, s99, s2
	s_and_b32 s100, s99, 7
	s_mul_i32 s100, s100, 0x160
	s_lshr_b32 s101, s99, 3
	s_add_i32 s100, s100, s101
	s_mul_hi_u32 s101, s100, 0x1745d18
	s_lshl_b32 s101, s101, 3
	s_and_b32 s100, s100, 7
	s_or_b32 s101, s101, s100
	s_lshl_b32 s101, s101, 8
	v_add_u32_e32 v108, s101, v110
	v_lshlrev_b32_e32 v108, 6, v108
	v_mov_b32_e32 v109, 0
	v_lshl_add_u64 v[108:109], s[18:19], 0, v[108:109]
	global_load_dwordx4 v[44:47], v[108:109], off
	global_load_dwordx4 v[48:51], v[108:109], off offset:16
	global_load_dwordx4 v[52:55], v[108:109], off offset:32
	global_load_dwordx4 v[56:59], v[108:109], off offset:48
	s_add_i32 s98, s98, 2
	s_mul_i32 s99, s98, s72
	s_add_i32 s99, s99, s2
	s_cmp_lt_u32 s99, 0xb00
	s_cselect_b32 s99, s99, s2
	s_and_b32 s100, s99, 7
	s_mul_i32 s100, s100, 0x160
	s_lshr_b32 s101, s99, 3
	s_add_i32 s100, s100, s101
	s_mul_hi_u32 s101, s100, 0x1745d18
	s_lshl_b32 s101, s101, 3
	s_and_b32 s100, s100, 7
	s_or_b32 s101, s101, s100
	s_lshl_b32 s101, s101, 8
	v_add_u32_e32 v108, s101, v110
	v_lshlrev_b32_e32 v108, 6, v108
	v_mov_b32_e32 v109, 0
	v_lshl_add_u64 v[108:109], s[18:19], 0, v[108:109]
	global_load_dwordx4 v[60:63], v[108:109], off
	global_load_dwordx4 v[64:67], v[108:109], off offset:16
	global_load_dwordx4 v[68:71], v[108:109], off offset:32
	global_load_dwordx4 v[72:75], v[108:109], off offset:48
	s_add_i32 s98, s98, 2
	s_mul_i32 s99, s98, s72
	s_add_i32 s99, s99, s2
	s_cmp_lt_u32 s99, 0xb00
	s_cselect_b32 s99, s99, s2
	s_and_b32 s100, s99, 7
	s_mul_i32 s100, s100, 0x160
	s_lshr_b32 s101, s99, 3
	s_add_i32 s100, s100, s101
	s_mul_hi_u32 s101, s100, 0x1745d18
	s_lshl_b32 s101, s101, 3
	s_and_b32 s100, s100, 7
	s_or_b32 s101, s101, s100
	s_lshl_b32 s101, s101, 8
	v_add_u32_e32 v108, s101, v110
	v_lshlrev_b32_e32 v108, 6, v108
	v_mov_b32_e32 v109, 0
	v_lshl_add_u64 v[108:109], s[18:19], 0, v[108:109]
	global_load_dwordx4 v[76:79], v[108:109], off
	global_load_dwordx4 v[80:83], v[108:109], off offset:16
	global_load_dwordx4 v[84:87], v[108:109], off offset:32
	global_load_dwordx4 v[88:91], v[108:109], off offset:48
	s_add_i32 s98, s98, 2
	s_mul_i32 s99, s98, s72
	s_add_i32 s99, s99, s2
	s_cmp_lt_u32 s99, 0xb00
	s_cselect_b32 s99, s99, s2
	s_and_b32 s100, s99, 7
	s_mul_i32 s100, s100, 0x160
	s_lshr_b32 s101, s99, 3
	s_add_i32 s100, s100, s101
	s_mul_hi_u32 s101, s100, 0x1745d18
	s_lshl_b32 s101, s101, 3
	s_and_b32 s100, s100, 7
	s_or_b32 s101, s101, s100
	s_lshl_b32 s101, s101, 8
	v_add_u32_e32 v108, s101, v110
	v_lshlrev_b32_e32 v108, 6, v108
	v_mov_b32_e32 v109, 0
	v_lshl_add_u64 v[108:109], s[18:19], 0, v[108:109]
	global_load_dwordx4 v[92:95], v[108:109], off
	global_load_dwordx4 v[96:99], v[108:109], off offset:16
	global_load_dwordx4 v[100:103], v[108:109], off offset:32
	global_load_dwordx4 v[104:107], v[108:109], off offset:48
	s_add_i32 s98, s98, 2
	v_lshlrev_b32_e32 v112, 2, v128
	v_add_u32_e32 v112, 0x20000, v112
	s_waitcnt vmcnt(20)
	v_pk_add_f32 v[114:115], v[14:15], v[18:19]
	v_pk_add_f32 v[116:117], v[12:13], v[16:17]
	v_pk_add_f32 v[118:119], v[22:23], v[26:27]
	v_pk_add_f32 v[120:121], v[20:21], v[24:25]
	v_pk_add_f32 v[114:115], v[114:115], v[118:119]
	v_pk_add_f32 v[116:117], v[116:117], v[120:121]
	v_add_f32_e32 v116, v117, v116
	v_add_f32_e32 v114, v114, v115
	v_add_f32_e32 v114, v116, v114
	v_fmamk_f32 v114, v114, 0x3a800000, v111
	v_rsq_f32_e32 v114, v114
	ds_write_b32 v112, v114
	s_waitcnt vmcnt(16)
	v_pk_add_f32 v[114:115], v[30:31], v[34:35]
	v_pk_add_f32 v[116:117], v[28:29], v[32:33]
	v_pk_add_f32 v[118:119], v[38:39], v[42:43]
	v_pk_add_f32 v[120:121], v[36:37], v[40:41]
	v_pk_add_f32 v[114:115], v[114:115], v[118:119]
	v_pk_add_f32 v[116:117], v[116:117], v[120:121]
	v_add_f32_e32 v116, v117, v116
	v_add_f32_e32 v114, v114, v115
	v_add_f32_e32 v114, v116, v114
	v_fmamk_f32 v114, v114, 0x3a800000, v111
	v_rsq_f32_e32 v114, v114
	ds_write_b32 v112, v114 offset:2048
	s_waitcnt vmcnt(12)
	v_pk_add_f32 v[114:115], v[46:47], v[50:51]
	v_pk_add_f32 v[116:117], v[44:45], v[48:49]
	v_pk_add_f32 v[118:119], v[54:55], v[58:59]
	v_pk_add_f32 v[120:121], v[52:53], v[56:57]
	v_pk_add_f32 v[114:115], v[114:115], v[118:119]
	v_pk_add_f32 v[116:117], v[116:117], v[120:121]
	v_add_f32_e32 v116, v117, v116
	v_add_f32_e32 v114, v114, v115
	v_add_f32_e32 v114, v116, v114
	v_fmamk_f32 v114, v114, 0x3a800000, v111
	v_rsq_f32_e32 v114, v114
	ds_write_b32 v112, v114 offset:4096
	s_waitcnt vmcnt(8)
	v_pk_add_f32 v[114:115], v[62:63], v[66:67]
	v_pk_add_f32 v[116:117], v[60:61], v[64:65]
	v_pk_add_f32 v[118:119], v[70:71], v[74:75]
	v_pk_add_f32 v[120:121], v[68:69], v[72:73]
	v_pk_add_f32 v[114:115], v[114:115], v[118:119]
	v_pk_add_f32 v[116:117], v[116:117], v[120:121]
	v_add_f32_e32 v116, v117, v116
	v_add_f32_e32 v114, v114, v115
	v_add_f32_e32 v114, v116, v114
	v_fmamk_f32 v114, v114, 0x3a800000, v111
	v_rsq_f32_e32 v114, v114
	ds_write_b32 v112, v114 offset:6144
	s_waitcnt vmcnt(4)
	v_pk_add_f32 v[114:115], v[78:79], v[82:83]
	v_pk_add_f32 v[116:117], v[76:77], v[80:81]
	v_pk_add_f32 v[118:119], v[86:87], v[90:91]
	v_pk_add_f32 v[120:121], v[84:85], v[88:89]
	v_pk_add_f32 v[114:115], v[114:115], v[118:119]
	v_pk_add_f32 v[116:117], v[116:117], v[120:121]
	v_add_f32_e32 v116, v117, v116
	v_add_f32_e32 v114, v114, v115
	v_add_f32_e32 v114, v116, v114
	v_fmamk_f32 v114, v114, 0x3a800000, v111
	v_rsq_f32_e32 v114, v114
	ds_write_b32 v112, v114 offset:8192
	s_waitcnt vmcnt(0)
	v_pk_add_f32 v[114:115], v[94:95], v[98:99]
	v_pk_add_f32 v[116:117], v[92:93], v[96:97]
	v_pk_add_f32 v[118:119], v[102:103], v[106:107]
	v_pk_add_f32 v[120:121], v[100:101], v[104:105]
	v_pk_add_f32 v[114:115], v[114:115], v[118:119]
	v_pk_add_f32 v[116:117], v[116:117], v[120:121]
	v_add_f32_e32 v116, v117, v116
	v_add_f32_e32 v114, v114, v115
	v_add_f32_e32 v114, v116, v114
	v_fmamk_f32 v114, v114, 0x3a800000, v111
	v_rsq_f32_e32 v114, v114
	ds_write_b32 v112, v114 offset:10240

.LBB0_1809:
	s_cmp_lt_i32 s74, 20
	s_cselect_b64 s[0:1], -1, 0
	s_cmp_gt_i32 s75, 19
	s_cselect_b64 s[4:5], -1, 0
	s_and_b64 s[0:1], s[0:1], s[4:5]
	s_andn2_b64 vcc, exec, s[0:1]
	s_cbranch_vccnz .LBB0_1918
	s_waitcnt vmcnt(0)
	v_lshlrev_b32_e32 v8, 2, v128
	s_ashr_i32 s3, s2, 31
	v_add_u32_e32 v0, 0, v8
	s_ashr_i32 s48, s72, 31
	s_mov_b32 s49, s72
	v_and_b32_e32 v4, 0xff, v128
	v_add_u32_e32 v5, 0xfffffe00, v128
	v_add_u32_e32 v6, 0x20000, v0
	v_lshrrev_b32_e32 v7, 8, v128
	s_mov_b64 s[0:1], 0
	s_waitcnt lgkmcnt(0)
	v_mov_b64_e32 v[0:1], s[2:3]
	s_mov_b64 s[4:5], 0x600
	s_mov_b32 s10, 0x2aaaaaab
	s_movk_i32 s11, 0x60
	v_mov_b32_e32 v9, 0x358637bd
	s_movk_i32 s12, 0x8ff
	v_mov_b32_e32 v10, 0xc0
	v_mov_b32_e32 v11, 0xc1
	v_and_b32_e32 v110, 0xff, v128
	s_lshr_b32 s98, s91, 2
	v_mov_b32_e32 v111, 0x358637bd
	s_mul_i32 s99, s98, s72
	s_add_i32 s99, s99, s2
	s_cmp_lt_u32 s99, 0x600
	s_cselect_b32 s99, s99, s2
	s_and_b32 s100, s99, 7
	s_mul_i32 s100, s100, 0xc0
	s_lshr_b32 s101, s99, 3
	s_add_i32 s100, s100, s101
	s_mul_hi_u32 s101, s100, 0x2aaaaab
	s_lshl_b32 s101, s101, 3
	s_and_b32 s100, s100, 7
	s_or_b32 s101, s101, s100
	s_lshl_b32 s101, s101, 8
	v_add_u32_e32 v108, s101, v110
	v_lshlrev_b32_e32 v108, 6, v108
	v_mov_b32_e32 v109, 0
	v_lshl_add_u64 v[108:109], s[18:19], 0, v[108:109]
	global_load_dwordx4 v[12:15], v[108:109], off
	global_load_dwordx4 v[16:19], v[108:109], off offset:16
	global_load_dwordx4 v[20:23], v[108:109], off offset:32
	global_load_dwordx4 v[24:27], v[108:109], off offset:48
	s_add_i32 s98, s98, 2
	s_mul_i32 s99, s98, s72
	s_add_i32 s99, s99, s2
	s_cmp_lt_u32 s99, 0x600
	s_cselect_b32 s99, s99, s2
	s_and_b32 s100, s99, 7
	s_mul_i32 s100, s100, 0xc0
	s_lshr_b32 s101, s99, 3
	s_add_i32 s100, s100, s101
	s_mul_hi_u32 s101, s100, 0x2aaaaab
	s_lshl_b32 s101, s101, 3
	s_and_b32 s100, s100, 7
	s_or_b32 s101, s101, s100
	s_lshl_b32 s101, s101, 8
	v_add_u32_e32 v108, s101, v110
	v_lshlrev_b32_e32 v108, 6, v108
	v_mov_b32_e32 v109, 0
	v_lshl_add_u64 v[108:109], s[18:19], 0, v[108:109]
	global_load_dwordx4 v[28:31], v[108:109], off
	global_load_dwordx4 v[32:35], v[108:109], off offset:16
	global_load_dwordx4 v[36:39], v[108:109], off offset:32
	global_load_dwordx4 v[40:43], v[108:109], off offset:48
	s_add_i32 s98, s98, 2
	s_mul_i32 s99, s98, s72
	s_add_i32 s99, s99, s2
	s_cmp_lt_u32 s99, 0x600
	s_cselect_b32 s99, s99, s2
	s_and_b32 s100, s99, 7
	s_mul_i32 s100, s100, 0xc0
	s_lshr_b32 s101, s99, 3
	s_add_i32 s100, s100, s101
	s_mul_hi_u32 s101, s100, 0x2aaaaab
	s_lshl_b32 s101, s101, 3
	s_and_b32 s100, s100, 7
	s_or_b32 s101, s101, s100
	s_lshl_b32 s101, s101, 8
	v_add_u32_e32 v108, s101, v110
	v_lshlrev_b32_e32 v108, 6, v108
	v_mov_b32_e32 v109, 0
	v_lshl_add_u64 v[108:109], s[18:19], 0, v[108:109]
	global_load_dwordx4 v[44:47], v[108:109], off
	global_load_dwordx4 v[48:51], v[108:109], off offset:16
	global_load_dwordx4 v[52:55], v[108:109], off offset:32
	global_load_dwordx4 v[56:59], v[108:109], off offset:48
	s_add_i32 s98, s98, 2
	v_lshlrev_b32_e32 v112, 2, v128
	v_add_u32_e32 v112, 0x20000, v112
	s_waitcnt vmcnt(8)
	v_pk_add_f32 v[114:115], v[14:15], v[18:19]
	v_pk_add_f32 v[116:117], v[12:13], v[16:17]
	v_pk_add_f32 v[118:119], v[22:23], v[26:27]
	v_pk_add_f32 v[120:121], v[20:21], v[24:25]
	v_pk_add_f32 v[114:115], v[114:115], v[118:119]
	v_pk_add_f32 v[116:117], v[116:117], v[120:121]
	v_add_f32_e32 v116, v117, v116
	v_add_f32_e32 v114, v114, v115
	v_add_f32_e32 v114, v116, v114
	v_fmamk_f32 v114, v114, 0x3a800000, v111
	v_rsq_f32_e32 v114, v114
	ds_write_b32 v112, v114
	s_waitcnt vmcnt(4)
	v_pk_add_f32 v[114:115], v[30:31], v[34:35]
	v_pk_add_f32 v[116:117], v[28:29], v[32:33]
	v_pk_add_f32 v[118:119], v[38:39], v[42:43]
	v_pk_add_f32 v[120:121], v[36:37], v[40:41]
	v_pk_add_f32 v[114:115], v[114:115], v[118:119]
	v_pk_add_f32 v[116:117], v[116:117], v[120:121]
	v_add_f32_e32 v116, v117, v116
	v_add_f32_e32 v114, v114, v115
	v_add_f32_e32 v114, v116, v114
	v_fmamk_f32 v114, v114, 0x3a800000, v111
	v_rsq_f32_e32 v114, v114
	ds_write_b32 v112, v114 offset:2048
	s_waitcnt vmcnt(0)
	v_pk_add_f32 v[114:115], v[46:47], v[50:51]
	v_pk_add_f32 v[116:117], v[44:45], v[48:49]
	v_pk_add_f32 v[118:119], v[54:55], v[58:59]
	v_pk_add_f32 v[120:121], v[52:53], v[56:57]
	v_pk_add_f32 v[114:115], v[114:115], v[118:119]
	v_pk_add_f32 v[116:117], v[116:117], v[120:121]
	v_add_f32_e32 v116, v117, v116
	v_add_f32_e32 v114, v114, v115
	v_add_f32_e32 v114, v116, v114
	v_fmamk_f32 v114, v114, 0x3a800000, v111
	v_rsq_f32_e32 v114, v114
	ds_write_b32 v112, v114 offset:4096

.LBB0_2077:
	s_cmp_lt_i32 s74, 23
	s_cselect_b64 s[0:1], -1, 0
	s_cmp_gt_i32 s75, 22
	s_cselect_b64 s[4:5], -1, 0
	s_and_b64 s[0:1], s[0:1], s[4:5]
	s_andn2_b64 vcc, exec, s[0:1]
	s_cbranch_vccnz .LBB0_2152
	s_waitcnt vmcnt(0)
	v_lshlrev_b32_e32 v8, 2, v128
	s_ashr_i32 s3, s2, 31
	v_add_u32_e32 v0, 0, v8
	s_ashr_i32 s36, s72, 31
	s_mov_b32 s37, s72
	v_and_b32_e32 v4, 0xff, v128
	v_add_u32_e32 v5, 0xfffffe00, v128
	v_add_u32_e32 v6, 0x20000, v0
	s_mov_b64 s[0:1], 0
	s_waitcnt lgkmcnt(0)
	v_mov_b64_e32 v[0:1], s[2:3]
	s_mov_b64 s[4:5], 0xb00
	s_mov_b32 s10, 0x2e8ba2e9
	s_movk_i32 s11, 0xb0
	v_mov_b32_e32 v7, 0x358637bd
	s_movk_i32 s12, 0x8ff
	v_mov_b32_e32 v9, 0x160
	v_mov_b32_e32 v10, 0x161
	v_and_b32_e32 v110, 0xff, v128
	s_lshr_b32 s98, s91, 2
	v_mov_b32_e32 v111, 0x358637bd
	s_mul_i32 s99, s98, s72
	s_add_i32 s99, s99, s2
	s_cmp_lt_u32 s99, 0xb00
	s_cselect_b32 s99, s99, s2
	s_and_b32 s100, s99, 7
	s_mul_i32 s100, s100, 0x160
	s_lshr_b32 s101, s99, 3
	s_add_i32 s100, s100, s101
	s_mul_hi_u32 s101, s100, 0x1745d18
	s_lshl_b32 s101, s101, 3
	s_and_b32 s100, s100, 7
	s_or_b32 s101, s101, s100
	s_lshl_b32 s101, s101, 8
	v_add_u32_e32 v108, s101, v110
	v_lshlrev_b32_e32 v108, 6, v108
	v_mov_b32_e32 v109, 0
	v_lshl_add_u64 v[108:109], s[18:19], 0, v[108:109]
	global_load_dwordx4 v[12:15], v[108:109], off
	global_load_dwordx4 v[16:19], v[108:109], off offset:16
	global_load_dwordx4 v[20:23], v[108:109], off offset:32
	global_load_dwordx4 v[24:27], v[108:109], off offset:48
	s_add_i32 s98, s98, 2
	s_mul_i32 s99, s98, s72
	s_add_i32 s99, s99, s2
	s_cmp_lt_u32 s99, 0xb00
	s_cselect_b32 s99, s99, s2
	s_and_b32 s100, s99, 7
	s_mul_i32 s100, s100, 0x160
	s_lshr_b32 s101, s99, 3
	s_add_i32 s100, s100, s101
	s_mul_hi_u32 s101, s100, 0x1745d18
	s_lshl_b32 s101, s101, 3
	s_and_b32 s100, s100, 7
	s_or_b32 s101, s101, s100
	s_lshl_b32 s101, s101, 8
	v_add_u32_e32 v108, s101, v110
	v_lshlrev_b32_e32 v108, 6, v108
	v_mov_b32_e32 v109, 0
	v_lshl_add_u64 v[108:109], s[18:19], 0, v[108:109]
	global_load_dwordx4 v[28:31], v[108:109], off
	global_load_dwordx4 v[32:35], v[108:109], off offset:16
	global_load_dwordx4 v[36:39], v[108:109], off offset:32
	global_load_dwordx4 v[40:43], v[108:109], off offset:48
	s_add_i32 s98, s98, 2
	s_mul_i32 s99, s98, s72
	s_add_i32 s99, s99, s2
	s_cmp_lt_u32 s99, 0xb00
	s_cselect_b32 s99, s99, s2
	s_and_b32 s100, s99, 7
	s_mul_i32 s100, s100, 0x160
	s_lshr_b32 s101, s99, 3
	s_add_i32 s100, s100, s101
	s_mul_hi_u32 s101, s100, 0x1745d18
	s_lshl_b32 s101, s101, 3
	s_and_b32 s100, s100, 7
	s_or_b32 s101, s101, s100
	s_lshl_b32 s101, s101, 8
	v_add_u32_e32 v108, s101, v110
	v_lshlrev_b32_e32 v108, 6, v108
	v_mov_b32_e32 v109, 0
	v_lshl_add_u64 v[108:109], s[18:19], 0, v[108:109]
	global_load_dwordx4 v[44:47], v[108:109], off
	global_load_dwordx4 v[48:51], v[108:109], off offset:16
	global_load_dwordx4 v[52:55], v[108:109], off offset:32
	global_load_dwordx4 v[56:59], v[108:109], off offset:48
	s_add_i32 s98, s98, 2
	s_mul_i32 s99, s98, s72
	s_add_i32 s99, s99, s2
	s_cmp_lt_u32 s99, 0xb00
	s_cselect_b32 s99, s99, s2
	s_and_b32 s100, s99, 7
	s_mul_i32 s100, s100, 0x160
	s_lshr_b32 s101, s99, 3
	s_add_i32 s100, s100, s101
	s_mul_hi_u32 s101, s100, 0x1745d18
	s_lshl_b32 s101, s101, 3
	s_and_b32 s100, s100, 7
	s_or_b32 s101, s101, s100
	s_lshl_b32 s101, s101, 8
	v_add_u32_e32 v108, s101, v110
	v_lshlrev_b32_e32 v108, 6, v108
	v_mov_b32_e32 v109, 0
	v_lshl_add_u64 v[108:109], s[18:19], 0, v[108:109]
	global_load_dwordx4 v[60:63], v[108:109], off
	global_load_dwordx4 v[64:67], v[108:109], off offset:16
	global_load_dwordx4 v[68:71], v[108:109], off offset:32
	global_load_dwordx4 v[72:75], v[108:109], off offset:48
	s_add_i32 s98, s98, 2
	s_mul_i32 s99, s98, s72
	s_add_i32 s99, s99, s2
	s_cmp_lt_u32 s99, 0xb00
	s_cselect_b32 s99, s99, s2
	s_and_b32 s100, s99, 7
	s_mul_i32 s100, s100, 0x160
	s_lshr_b32 s101, s99, 3
	s_add_i32 s100, s100, s101
	s_mul_hi_u32 s101, s100, 0x1745d18
	s_lshl_b32 s101, s101, 3
	s_and_b32 s100, s100, 7
	s_or_b32 s101, s101, s100
	s_lshl_b32 s101, s101, 8
	v_add_u32_e32 v108, s101, v110
	v_lshlrev_b32_e32 v108, 6, v108
	v_mov_b32_e32 v109, 0
	v_lshl_add_u64 v[108:109], s[18:19], 0, v[108:109]
	global_load_dwordx4 v[76:79], v[108:109], off
	global_load_dwordx4 v[80:83], v[108:109], off offset:16
	global_load_dwordx4 v[84:87], v[108:109], off offset:32
	global_load_dwordx4 v[88:91], v[108:109], off offset:48
	s_add_i32 s98, s98, 2
	s_mul_i32 s99, s98, s72
	s_add_i32 s99, s99, s2
	s_cmp_lt_u32 s99, 0xb00
	s_cselect_b32 s99, s99, s2
	s_and_b32 s100, s99, 7
	s_mul_i32 s100, s100, 0x160
	s_lshr_b32 s101, s99, 3
	s_add_i32 s100, s100, s101
	s_mul_hi_u32 s101, s100, 0x1745d18
	s_lshl_b32 s101, s101, 3
	s_and_b32 s100, s100, 7
	s_or_b32 s101, s101, s100
	s_lshl_b32 s101, s101, 8
	v_add_u32_e32 v108, s101, v110
	v_lshlrev_b32_e32 v108, 6, v108
	v_mov_b32_e32 v109, 0
	v_lshl_add_u64 v[108:109], s[18:19], 0, v[108:109]
	global_load_dwordx4 v[92:95], v[108:109], off
	global_load_dwordx4 v[96:99], v[108:109], off offset:16
	global_load_dwordx4 v[100:103], v[108:109], off offset:32
	global_load_dwordx4 v[104:107], v[108:109], off offset:48
	s_add_i32 s98, s98, 2
	v_lshlrev_b32_e32 v112, 2, v128
	v_add_u32_e32 v112, 0x20000, v112
	s_waitcnt vmcnt(20)
	v_pk_add_f32 v[114:115], v[14:15], v[18:19]
	v_pk_add_f32 v[116:117], v[12:13], v[16:17]
	v_pk_add_f32 v[118:119], v[22:23], v[26:27]
	v_pk_add_f32 v[120:121], v[20:21], v[24:25]
	v_pk_add_f32 v[114:115], v[114:115], v[118:119]
	v_pk_add_f32 v[116:117], v[116:117], v[120:121]
	v_add_f32_e32 v116, v117, v116
	v_add_f32_e32 v114, v114, v115
	v_add_f32_e32 v114, v116, v114
	v_fmamk_f32 v114, v114, 0x3a800000, v111
	v_rsq_f32_e32 v114, v114
	ds_write_b32 v112, v114
	s_waitcnt vmcnt(16)
	v_pk_add_f32 v[114:115], v[30:31], v[34:35]
	v_pk_add_f32 v[116:117], v[28:29], v[32:33]
	v_pk_add_f32 v[118:119], v[38:39], v[42:43]
	v_pk_add_f32 v[120:121], v[36:37], v[40:41]
	v_pk_add_f32 v[114:115], v[114:115], v[118:119]
	v_pk_add_f32 v[116:117], v[116:117], v[120:121]
	v_add_f32_e32 v116, v117, v116
	v_add_f32_e32 v114, v114, v115
	v_add_f32_e32 v114, v116, v114
	v_fmamk_f32 v114, v114, 0x3a800000, v111
	v_rsq_f32_e32 v114, v114
	ds_write_b32 v112, v114 offset:2048
	s_waitcnt vmcnt(12)
	v_pk_add_f32 v[114:115], v[46:47], v[50:51]
	v_pk_add_f32 v[116:117], v[44:45], v[48:49]
	v_pk_add_f32 v[118:119], v[54:55], v[58:59]
	v_pk_add_f32 v[120:121], v[52:53], v[56:57]
	v_pk_add_f32 v[114:115], v[114:115], v[118:119]
	v_pk_add_f32 v[116:117], v[116:117], v[120:121]
	v_add_f32_e32 v116, v117, v116
	v_add_f32_e32 v114, v114, v115
	v_add_f32_e32 v114, v116, v114
	v_fmamk_f32 v114, v114, 0x3a800000, v111
	v_rsq_f32_e32 v114, v114
	ds_write_b32 v112, v114 offset:4096
	s_waitcnt vmcnt(8)
	v_pk_add_f32 v[114:115], v[62:63], v[66:67]
	v_pk_add_f32 v[116:117], v[60:61], v[64:65]
	v_pk_add_f32 v[118:119], v[70:71], v[74:75]
	v_pk_add_f32 v[120:121], v[68:69], v[72:73]
	v_pk_add_f32 v[114:115], v[114:115], v[118:119]
	v_pk_add_f32 v[116:117], v[116:117], v[120:121]
	v_add_f32_e32 v116, v117, v116
	v_add_f32_e32 v114, v114, v115
	v_add_f32_e32 v114, v116, v114
	v_fmamk_f32 v114, v114, 0x3a800000, v111
	v_rsq_f32_e32 v114, v114
	ds_write_b32 v112, v114 offset:6144
	s_waitcnt vmcnt(4)
	v_pk_add_f32 v[114:115], v[78:79], v[82:83]
	v_pk_add_f32 v[116:117], v[76:77], v[80:81]
	v_pk_add_f32 v[118:119], v[86:87], v[90:91]
	v_pk_add_f32 v[120:121], v[84:85], v[88:89]
	v_pk_add_f32 v[114:115], v[114:115], v[118:119]
	v_pk_add_f32 v[116:117], v[116:117], v[120:121]
	v_add_f32_e32 v116, v117, v116
	v_add_f32_e32 v114, v114, v115
	v_add_f32_e32 v114, v116, v114
	v_fmamk_f32 v114, v114, 0x3a800000, v111
	v_rsq_f32_e32 v114, v114
	ds_write_b32 v112, v114 offset:8192
	s_waitcnt vmcnt(0)
	v_pk_add_f32 v[114:115], v[94:95], v[98:99]
	v_pk_add_f32 v[116:117], v[92:93], v[96:97]
	v_pk_add_f32 v[118:119], v[102:103], v[106:107]
	v_pk_add_f32 v[120:121], v[100:101], v[104:105]
	v_pk_add_f32 v[114:115], v[114:115], v[118:119]
	v_pk_add_f32 v[116:117], v[116:117], v[120:121]
	v_add_f32_e32 v116, v117, v116
	v_add_f32_e32 v114, v114, v115
	v_add_f32_e32 v114, v116, v114
	v_fmamk_f32 v114, v114, 0x3a800000, v111
	v_rsq_f32_e32 v114, v114
	ds_write_b32 v112, v114 offset:10240
